# E34: SwiGLU phases prefetch the unit's row statistics into spare LDS by one LDS-DMA per wave at unit start; epilogue reads them with ds_read_b64 (no global-load latency behind vmcnt(0), stale vmcnt wa
# baseline (speedup 1.0000x reference)
.LBB0_303:
	s_lshl_b32 s18, s91, 20
	s_and_b64 s[8:9], s[34:35], exec
	s_cselect_b32 s8, s18, s94
	s_lshl_b32 s19, s90, 20
	s_and_b64 s[42:43], s[34:35], exec
	s_cselect_b32 s9, s19, s95
	s_add_i32 s94, s94, 0x80080
	s_addk_i32 s95, 0x100
	s_mov_b32 vcc_lo, -2
	v_mbcnt_lo_u32_b32 v206, -1, 0
	v_mbcnt_hi_u32_b32 v206, -1, v206
	s_add_i32 s43, s72, 0x16000
	v_and_b32_e32 v207, 31, v206
	v_and_b32_e32 v208, 32, v206
	v_and_b32_e32 v206, 15, v206
	s_mov_b32 m0, s43
	v_lshlrev_b32_e32 v207, 4, v207
	v_lshlrev_b32_e32 v206, 3, v206
	v_lshl_or_b32 v207, v208, 5, v207
	v_add_u32_e32 v206, s43, v206
	s_lshl_b32 s42, s93, 8
	s_add_i32 s42, s42, s46
	s_lshl_b32 s42, s42, 3
	v_readlane_b32 s43, v252, 58
	s_nop 0
	s_add_u32 s42, s43, s42
	v_readlane_b32 s43, v252, 59
	s_nop 0
	s_addc_u32 s43, s43, 0
	global_load_lds_dwordx4 v207, s[42:43]
	ds_read_b128 v[142:145], v136
	ds_read_b128 v[170:173], v136 offset:1024
	ds_read_b128 v[174:177], v136 offset:2048
	ds_read_b128 v[178:181], v136 offset:3072
	ds_read_b128 v[182:185], v137
	ds_read_b128 v[186:189], v137 offset:1024
	ds_read_b128 v[190:193], v137 offset:2048
	ds_read_b128 v[194:197], v137 offset:3072
	s_add_i32 s42, s94, 0xfff80080
	s_cmp_eq_u32 vcc_lo, 28
	s_cselect_b32 s97, s8, s42
	s_cselect_b32 s52, s9, s95
	s_or_b32 vcc_hi, s97, 0x80
	s_mov_b32 m0, s72
	ds_read_b128 v[198:201], v138
	ds_read_b128 v[202:205], v138 offset:1024
	ds_read_b128 v[228:231], v138 offset:2048
	ds_read_b128 v[232:235], v138 offset:3072
	ds_read_b128 v[236:239], v138 offset:4096
	ds_read_b128 v[240:243], v138 offset:5120
	ds_read_b128 v[244:247], v138 offset:6144
	ds_read_b128 v[248:251], v138 offset:7168
	buffer_load_dwordx4 v132, s[60:63], s94 offen lds
	s_mov_b32 m0, s47
	s_nop 0
	buffer_load_dwordx4 v134, s[60:63], s94 offen lds
	s_waitcnt vmcnt(8)
	s_waitcnt lgkmcnt(0)
	s_setprio 1
	s_barrier
	v_mfma_f32_16x16x32_bf16 v[114:117], v[142:145], v[198:201], 0
	v_mfma_f32_16x16x32_bf16 v[114:117], v[170:173], v[202:205], v[114:117]
	v_mfma_f32_16x16x32_bf16 v[110:113], v[174:177], v[198:201], 0
	v_mfma_f32_16x16x32_bf16 v[110:113], v[178:181], v[202:205], v[110:113]
	v_mfma_f32_16x16x32_bf16 v[122:125], v[190:193], v[198:201], 0
	v_mfma_f32_16x16x32_bf16 v[122:125], v[194:197], v[202:205], v[122:125]
	v_mfma_f32_16x16x32_bf16 v[126:129], v[182:185], v[198:201], 0
	v_mfma_f32_16x16x32_bf16 v[126:129], v[186:189], v[202:205], v[126:129]
	v_mfma_f32_16x16x32_bf16 v[118:121], v[182:185], v[228:231], 0
	v_mfma_f32_16x16x32_bf16 v[118:121], v[186:189], v[232:235], v[118:121]
	v_mfma_f32_16x16x32_bf16 v[98:101], v[190:193], v[228:231], 0
	v_mfma_f32_16x16x32_bf16 v[98:101], v[194:197], v[232:235], v[98:101]
	v_mfma_f32_16x16x32_bf16 v[102:105], v[174:177], v[228:231], 0
	v_mfma_f32_16x16x32_bf16 v[102:105], v[178:181], v[232:235], v[102:105]
	v_mfma_f32_16x16x32_bf16 v[106:109], v[142:145], v[228:231], 0
	v_mfma_f32_16x16x32_bf16 v[106:109], v[170:173], v[232:235], v[106:109]
	v_mfma_f32_16x16x32_bf16 v[94:97], v[142:145], v[236:239], 0
	v_mfma_f32_16x16x32_bf16 v[94:97], v[170:173], v[240:243], v[94:97]
	v_mfma_f32_16x16x32_bf16 v[86:89], v[174:177], v[236:239], 0
	v_mfma_f32_16x16x32_bf16 v[86:89], v[178:181], v[240:243], v[86:89]
	v_mfma_f32_16x16x32_bf16 v[82:85], v[190:193], v[236:239], 0
	v_mfma_f32_16x16x32_bf16 v[82:85], v[194:197], v[240:243], v[82:85]
	v_mfma_f32_16x16x32_bf16 v[90:93], v[182:185], v[236:239], 0
	v_mfma_f32_16x16x32_bf16 v[90:93], v[186:189], v[240:243], v[90:93]
	v_mfma_f32_16x16x32_bf16 v[74:77], v[182:185], v[244:247], 0
	v_mfma_f32_16x16x32_bf16 v[74:77], v[186:189], v[248:251], v[74:77]
	v_mfma_f32_16x16x32_bf16 v[66:69], v[190:193], v[244:247], 0
	v_mfma_f32_16x16x32_bf16 v[66:69], v[194:197], v[248:251], v[66:69]
	v_mfma_f32_16x16x32_bf16 v[70:73], v[174:177], v[244:247], 0
	v_mfma_f32_16x16x32_bf16 v[70:73], v[178:181], v[248:251], v[70:73]
	v_mfma_f32_16x16x32_bf16 v[78:81], v[142:145], v[244:247], 0
	v_mfma_f32_16x16x32_bf16 v[78:81], v[170:173], v[248:251], v[78:81]
	s_barrier
	s_setprio 0
	s_mov_b32 s42, s62
	s_mov_b32 s43, s63
	s_mov_b32 m0, s13
	ds_read_b128 v[198:201], v138 offset:16384
	buffer_load_dwordx4 v133, s[40:43], s52 offen lds
	s_add_i32 s96, s52, 0x80000
	s_mov_b32 m0, s14
	ds_read_b128 v[202:205], v138 offset:17408
	buffer_load_dwordx4 v135, s[40:43], s52 offen lds
	s_mov_b32 m0, s15
	ds_read_b128 v[228:231], v138 offset:18432
	buffer_load_dwordx4 v133, s[40:43], s96 offen lds
	s_mov_b32 m0, s16
	ds_read_b128 v[232:235], v138 offset:19456
	buffer_load_dwordx4 v135, s[40:43], s96 offen lds
	s_mov_b32 m0, s2
	ds_read_b128 v[236:239], v138 offset:20480
	buffer_load_dwordx4 v132, s[60:63], s97 offen lds
	s_mov_b32 m0, s21
	ds_read_b128 v[240:243], v138 offset:21504
	buffer_load_dwordx4 v134, s[60:63], s97 offen lds
	ds_read_b128 v[244:247], v138 offset:22528
	ds_read_b128 v[248:251], v138 offset:23552
	s_waitcnt vmcnt(8)
	s_waitcnt lgkmcnt(0)
	s_setprio 1
	s_barrier
	v_mfma_f32_16x16x32_bf16 v[62:65], v[142:145], v[198:201], 0
	v_mfma_f32_16x16x32_bf16 v[62:65], v[170:173], v[202:205], v[62:65]
	v_mfma_f32_16x16x32_bf16 v[54:57], v[174:177], v[198:201], 0
	v_mfma_f32_16x16x32_bf16 v[54:57], v[178:181], v[202:205], v[54:57]
	v_mfma_f32_16x16x32_bf16 v[50:53], v[190:193], v[198:201], 0
	v_mfma_f32_16x16x32_bf16 v[50:53], v[194:197], v[202:205], v[50:53]
	v_mfma_f32_16x16x32_bf16 v[58:61], v[182:185], v[198:201], 0
	v_mfma_f32_16x16x32_bf16 v[58:61], v[186:189], v[202:205], v[58:61]
	v_mfma_f32_16x16x32_bf16 v[42:45], v[182:185], v[228:231], 0
	v_mfma_f32_16x16x32_bf16 v[42:45], v[186:189], v[232:235], v[42:45]
	v_mfma_f32_16x16x32_bf16 v[34:37], v[190:193], v[228:231], 0
	v_mfma_f32_16x16x32_bf16 v[34:37], v[194:197], v[232:235], v[34:37]
	v_mfma_f32_16x16x32_bf16 v[38:41], v[174:177], v[228:231], 0
	v_mfma_f32_16x16x32_bf16 v[38:41], v[178:181], v[232:235], v[38:41]
	v_mfma_f32_16x16x32_bf16 v[46:49], v[142:145], v[228:231], 0
	v_mfma_f32_16x16x32_bf16 v[46:49], v[170:173], v[232:235], v[46:49]
	v_mfma_f32_16x16x32_bf16 v[30:33], v[142:145], v[236:239], 0
	v_mfma_f32_16x16x32_bf16 v[30:33], v[170:173], v[240:243], v[30:33]
	v_mfma_f32_16x16x32_bf16 v[22:25], v[174:177], v[236:239], 0
	v_mfma_f32_16x16x32_bf16 v[22:25], v[178:181], v[240:243], v[22:25]
	v_mfma_f32_16x16x32_bf16 v[18:21], v[190:193], v[236:239], 0
	v_mfma_f32_16x16x32_bf16 v[18:21], v[194:197], v[240:243], v[18:21]
	v_mfma_f32_16x16x32_bf16 v[26:29], v[182:185], v[236:239], 0
	v_mfma_f32_16x16x32_bf16 v[26:29], v[186:189], v[240:243], v[26:29]
	v_mfma_f32_16x16x32_bf16 v[10:13], v[182:185], v[244:247], 0
	v_mfma_f32_16x16x32_bf16 v[10:13], v[186:189], v[248:251], v[10:13]
	v_mfma_f32_16x16x32_bf16 v[2:5], v[190:193], v[244:247], 0
	v_mfma_f32_16x16x32_bf16 v[2:5], v[194:197], v[248:251], v[2:5]
	v_mfma_f32_16x16x32_bf16 v[6:9], v[174:177], v[244:247], 0
	v_mfma_f32_16x16x32_bf16 v[6:9], v[178:181], v[248:251], v[6:9]
	v_mfma_f32_16x16x32_bf16 v[14:17], v[142:145], v[244:247], 0
	v_mfma_f32_16x16x32_bf16 v[14:17], v[170:173], v[248:251], v[14:17]
	s_barrier
	s_setprio 0
	ds_read_b128 v[142:145], v139
	ds_read_b128 v[170:173], v139 offset:1024
	ds_read_b128 v[174:177], v139 offset:2048
	ds_read_b128 v[178:181], v139 offset:3072
	ds_read_b128 v[182:185], v140
	ds_read_b128 v[186:189], v140 offset:1024
	ds_read_b128 v[190:193], v140 offset:2048
	ds_read_b128 v[194:197], v140 offset:3072
	s_add_i32 s97, s97, 0x80000
	s_mov_b32 m0, s23
	ds_read_b128 v[198:201], v138 offset:32768
	ds_read_b128 v[202:205], v138 offset:33792
	ds_read_b128 v[228:231], v138 offset:34816
	ds_read_b128 v[232:235], v138 offset:35840
	ds_read_b128 v[236:239], v138 offset:36864
	ds_read_b128 v[240:243], v138 offset:37888
	ds_read_b128 v[244:247], v138 offset:38912
	ds_read_b128 v[248:251], v138 offset:39936
	buffer_load_dwordx4 v132, s[60:63], s97 offen lds
	s_mov_b32 m0, s24
	s_nop 0
	buffer_load_dwordx4 v134, s[60:63], s97 offen lds
	s_waitcnt vmcnt(8)
	s_waitcnt lgkmcnt(0)
	s_setprio 1
	s_barrier
	v_mfma_f32_16x16x32_bf16 v[114:117], v[142:145], v[198:201], v[114:117]
	v_mfma_f32_16x16x32_bf16 v[114:117], v[170:173], v[202:205], v[114:117]
	v_mfma_f32_16x16x32_bf16 v[110:113], v[174:177], v[198:201], v[110:113]
	v_mfma_f32_16x16x32_bf16 v[110:113], v[178:181], v[202:205], v[110:113]
	v_mfma_f32_16x16x32_bf16 v[122:125], v[190:193], v[198:201], v[122:125]
	v_mfma_f32_16x16x32_bf16 v[122:125], v[194:197], v[202:205], v[122:125]
	v_mfma_f32_16x16x32_bf16 v[126:129], v[182:185], v[198:201], v[126:129]
	v_mfma_f32_16x16x32_bf16 v[126:129], v[186:189], v[202:205], v[126:129]
	v_mfma_f32_16x16x32_bf16 v[118:121], v[182:185], v[228:231], v[118:121]
	v_mfma_f32_16x16x32_bf16 v[118:121], v[186:189], v[232:235], v[118:121]
	v_mfma_f32_16x16x32_bf16 v[98:101], v[190:193], v[228:231], v[98:101]
	v_mfma_f32_16x16x32_bf16 v[98:101], v[194:197], v[232:235], v[98:101]
	v_mfma_f32_16x16x32_bf16 v[102:105], v[174:177], v[228:231], v[102:105]
	v_mfma_f32_16x16x32_bf16 v[102:105], v[178:181], v[232:235], v[102:105]
	v_mfma_f32_16x16x32_bf16 v[106:109], v[142:145], v[228:231], v[106:109]
	v_mfma_f32_16x16x32_bf16 v[106:109], v[170:173], v[232:235], v[106:109]
	v_mfma_f32_16x16x32_bf16 v[94:97], v[142:145], v[236:239], v[94:97]
	v_mfma_f32_16x16x32_bf16 v[94:97], v[170:173], v[240:243], v[94:97]
	v_mfma_f32_16x16x32_bf16 v[86:89], v[174:177], v[236:239], v[86:89]
	v_mfma_f32_16x16x32_bf16 v[86:89], v[178:181], v[240:243], v[86:89]
	v_mfma_f32_16x16x32_bf16 v[82:85], v[190:193], v[236:239], v[82:85]
	v_mfma_f32_16x16x32_bf16 v[82:85], v[194:197], v[240:243], v[82:85]
	v_mfma_f32_16x16x32_bf16 v[90:93], v[182:185], v[236:239], v[90:93]
	v_mfma_f32_16x16x32_bf16 v[90:93], v[186:189], v[240:243], v[90:93]
	v_mfma_f32_16x16x32_bf16 v[74:77], v[182:185], v[244:247], v[74:77]
	v_mfma_f32_16x16x32_bf16 v[74:77], v[186:189], v[248:251], v[74:77]
	v_mfma_f32_16x16x32_bf16 v[66:69], v[190:193], v[244:247], v[66:69]
	v_mfma_f32_16x16x32_bf16 v[66:69], v[194:197], v[248:251], v[66:69]
	v_mfma_f32_16x16x32_bf16 v[70:73], v[174:177], v[244:247], v[70:73]
	v_mfma_f32_16x16x32_bf16 v[70:73], v[178:181], v[248:251], v[70:73]
	v_mfma_f32_16x16x32_bf16 v[78:81], v[142:145], v[244:247], v[78:81]
	v_mfma_f32_16x16x32_bf16 v[78:81], v[170:173], v[248:251], v[78:81]
	s_barrier
	s_setprio 0
	s_or_b32 s53, s52, 0x80
	s_mov_b32 m0, s31
	ds_read_b128 v[198:201], v138 offset:49152
	buffer_load_dwordx4 v133, s[40:43], s53 offen lds
	s_add_i32 s52, s52, 0x80080
	s_mov_b32 m0, s33
	ds_read_b128 v[202:205], v138 offset:50176
	buffer_load_dwordx4 v135, s[40:43], s53 offen lds
	s_mov_b32 m0, s68
	ds_read_b128 v[228:231], v138 offset:51200
	buffer_load_dwordx4 v133, s[40:43], s52 offen lds
	s_mov_b32 m0, s69
	ds_read_b128 v[232:235], v138 offset:52224
	buffer_load_dwordx4 v135, s[40:43], s52 offen lds
	s_mov_b32 m0, s36
	ds_read_b128 v[236:239], v138 offset:53248
	buffer_load_dwordx4 v132, s[60:63], vcc_hi offen lds
	s_mov_b32 m0, s37
	ds_read_b128 v[240:243], v138 offset:54272
	buffer_load_dwordx4 v134, s[60:63], vcc_hi offen lds
	ds_read_b128 v[244:247], v138 offset:55296
	ds_read_b128 v[248:251], v138 offset:56320
	s_waitcnt vmcnt(8)
	s_waitcnt lgkmcnt(0)
	s_setprio 1
	s_barrier
	v_mfma_f32_16x16x32_bf16 v[62:65], v[142:145], v[198:201], v[62:65]
	v_mfma_f32_16x16x32_bf16 v[62:65], v[170:173], v[202:205], v[62:65]
	v_mfma_f32_16x16x32_bf16 v[54:57], v[174:177], v[198:201], v[54:57]
	v_mfma_f32_16x16x32_bf16 v[54:57], v[178:181], v[202:205], v[54:57]
	v_mfma_f32_16x16x32_bf16 v[50:53], v[190:193], v[198:201], v[50:53]
	v_mfma_f32_16x16x32_bf16 v[50:53], v[194:197], v[202:205], v[50:53]
	v_mfma_f32_16x16x32_bf16 v[58:61], v[182:185], v[198:201], v[58:61]
	v_mfma_f32_16x16x32_bf16 v[58:61], v[186:189], v[202:205], v[58:61]
	v_mfma_f32_16x16x32_bf16 v[42:45], v[182:185], v[228:231], v[42:45]
	v_mfma_f32_16x16x32_bf16 v[42:45], v[186:189], v[232:235], v[42:45]
	v_mfma_f32_16x16x32_bf16 v[34:37], v[190:193], v[228:231], v[34:37]
	v_mfma_f32_16x16x32_bf16 v[34:37], v[194:197], v[232:235], v[34:37]
	v_mfma_f32_16x16x32_bf16 v[38:41], v[174:177], v[228:231], v[38:41]
	v_mfma_f32_16x16x32_bf16 v[38:41], v[178:181], v[232:235], v[38:41]
	v_mfma_f32_16x16x32_bf16 v[46:49], v[142:145], v[228:231], v[46:49]
	v_mfma_f32_16x16x32_bf16 v[46:49], v[170:173], v[232:235], v[46:49]
	v_mfma_f32_16x16x32_bf16 v[30:33], v[142:145], v[236:239], v[30:33]
	v_mfma_f32_16x16x32_bf16 v[30:33], v[170:173], v[240:243], v[30:33]
	v_mfma_f32_16x16x32_bf16 v[22:25], v[174:177], v[236:239], v[22:25]
	v_mfma_f32_16x16x32_bf16 v[22:25], v[178:181], v[240:243], v[22:25]
	v_mfma_f32_16x16x32_bf16 v[18:21], v[190:193], v[236:239], v[18:21]
	v_mfma_f32_16x16x32_bf16 v[18:21], v[194:197], v[240:243], v[18:21]
	v_mfma_f32_16x16x32_bf16 v[26:29], v[182:185], v[236:239], v[26:29]
	v_mfma_f32_16x16x32_bf16 v[26:29], v[186:189], v[240:243], v[26:29]
	v_mfma_f32_16x16x32_bf16 v[10:13], v[182:185], v[244:247], v[10:13]
	v_mfma_f32_16x16x32_bf16 v[10:13], v[186:189], v[248:251], v[10:13]
	v_mfma_f32_16x16x32_bf16 v[2:5], v[190:193], v[244:247], v[2:5]
	v_mfma_f32_16x16x32_bf16 v[2:5], v[194:197], v[248:251], v[2:5]
	v_mfma_f32_16x16x32_bf16 v[6:9], v[174:177], v[244:247], v[6:9]
	v_mfma_f32_16x16x32_bf16 v[6:9], v[178:181], v[248:251], v[6:9]
	v_mfma_f32_16x16x32_bf16 v[14:17], v[142:145], v[244:247], v[14:17]
	v_mfma_f32_16x16x32_bf16 v[14:17], v[170:173], v[248:251], v[14:17]
	s_barrier
	s_setprio 0
	s_add_i32 vcc_lo, vcc_lo, 2
	s_addk_i32 s94, 0x100
	s_addk_i32 s95, 0x100
	s_cmp_gt_u32 vcc_lo, 29

.LBB0_307:
	s_lshl_b32 s8, s93, 8
	s_add_i32 s8, s8, s46
	s_ashr_i32 s9, s8, 31
	v_lshl_add_u64 v[142:143], s[8:9], 3, v[130:131]
	ds_read_b64 v[144:145], v206
	ds_read_b64 v[154:155], v206 offset:128
	v_pk_mul_f32 v[156:157], v[114:115], v[126:127]
	v_pk_mul_f32 v[170:171], v[112:113], v[124:125]
	v_pk_mul_f32 v[172:173], v[110:111], v[122:123]
	v_pk_mul_f32 v[174:175], v[108:109], v[120:121]
	v_pk_mul_f32 v[176:177], v[106:107], v[118:119]
	ds_read_b64 v[178:179], v206 offset:256
	ds_read_b64 v[126:127], v206 offset:384
	ds_read_b64 v[124:125], v206 offset:512
	ds_read_b64 v[122:123], v206 offset:640
	ds_read_b64 v[120:121], v206 offset:768
	ds_read_b64 v[118:119], v206 offset:896
	s_flbit_i32_b32 s8, 0
	s_min_u32 s42, s8, 32
	s_mul_i32 s8, s93, 0x58
	s_sub_i32 s93, 32, s42
	v_pk_mul_f32 v[128:129], v[116:117], v[128:129]
	s_lshl_b32 s9, s92, 1
	s_or_b32 s9, s9, s73
	s_add_i32 s8, s9, s8
	s_ashr_i32 s9, s8, 31
	s_lshl_b64 s[8:9], s[8:9], 15
	s_add_u32 s43, s25, s8
	s_addc_u32 s92, s30, s9
	s_add_u32 s8, s43, s64
	s_addc_u32 s9, s92, s65
	s_add_u32 s8, s8, s88
	s_addc_u32 s9, s9, 0
	v_pk_mul_f32 v[98:99], v[102:103], v[98:99]
	v_pk_mul_f32 v[100:101], v[104:105], v[100:101]
	v_pk_mul_f32 v[90:91], v[94:95], v[90:91]
	v_pk_mul_f32 v[92:93], v[96:97], v[92:93]
	v_pk_mul_f32 v[82:83], v[86:87], v[82:83]
	v_pk_mul_f32 v[84:85], v[88:89], v[84:85]
	v_pk_mul_f32 v[74:75], v[78:79], v[74:75]
	v_pk_mul_f32 v[76:77], v[80:81], v[76:77]
	v_pk_mul_f32 v[66:67], v[70:71], v[66:67]
	v_pk_mul_f32 v[68:69], v[72:73], v[68:69]
	v_pk_mul_f32 v[58:59], v[62:63], v[58:59]
	v_pk_mul_f32 v[60:61], v[64:65], v[60:61]
	v_pk_mul_f32 v[50:51], v[54:55], v[50:51]
	v_pk_mul_f32 v[52:53], v[56:57], v[52:53]
	v_pk_mul_f32 v[42:43], v[46:47], v[42:43]
	v_pk_mul_f32 v[44:45], v[48:49], v[44:45]
	v_pk_mul_f32 v[34:35], v[38:39], v[34:35]
	v_pk_mul_f32 v[36:37], v[40:41], v[36:37]
	v_pk_mul_f32 v[26:27], v[30:31], v[26:27]
	v_pk_mul_f32 v[28:29], v[32:33], v[28:29]
	v_pk_mul_f32 v[18:19], v[22:23], v[18:19]
	v_pk_mul_f32 v[20:21], v[24:25], v[20:21]
	v_pk_mul_f32 v[12:13], v[16:17], v[12:13]
	v_pk_mul_f32 v[10:11], v[14:15], v[10:11]
	v_pk_mul_f32 v[4:5], v[8:9], v[4:5]
	v_pk_mul_f32 v[2:3], v[6:7], v[2:3]
	v_readlane_b32 s97, v252, 18
	v_readlane_b32 s96, v252, 46
	s_waitcnt lgkmcnt(0)
	v_mov_b32_e32 v146, v145
	v_lshlrev_b64 v[142:143], s42, v[146:147]
	v_min_u32_e32 v142, 1, v142
	v_mov_b32_e32 v146, v155
	v_or_b32_e32 v143, v143, v142
	v_cvt_f32_u32_e32 v180, v144
	v_lshlrev_b64 v[144:145], s42, v[146:147]
	v_cvt_f32_u32_e32 v143, v143
	v_min_u32_e32 v146, 1, v144
	v_or_b32_e32 v145, v145, v146
	v_cvt_f32_u32_e32 v154, v154
	v_cvt_f32_u32_e32 v145, v145
	v_fmamk_f32 v142, v180, 0x30000000, v209
	v_ldexp_f32 v143, v143, s93
	v_fmac_f32_e32 v142, 2.0, v143
	v_rsq_f32_e32 v143, v142
	v_fmamk_f32 v144, v154, 0x30000000, v209
	v_ldexp_f32 v145, v145, s93
	v_fmac_f32_e32 v144, 2.0, v145
	v_rsq_f32_e32 v145, v144
	v_mul_f32_e32 v146, 0xbfb8aa3b, v143
	v_pk_mul_f32 v[114:115], v[114:115], v[146:147] op_sel_hi:[1,0]
	v_pk_mul_f32 v[116:117], v[116:117], v[146:147] op_sel_hi:[1,0]
	v_exp_f32_e32 v114, v114
	v_exp_f32_e32 v115, v115
	v_pk_mul_f32 v[110:111], v[110:111], v[146:147] op_sel_hi:[1,0]
	v_pk_mul_f32 v[112:113], v[112:113], v[146:147] op_sel_hi:[1,0]
	v_mul_f32_e32 v146, 0xbfb8aa3b, v145
	v_exp_f32_e32 v116, v116
	v_exp_f32_e32 v117, v117
	v_exp_f32_e32 v110, v110
	v_exp_f32_e32 v111, v111
	v_exp_f32_e32 v112, v112
	v_exp_f32_e32 v113, v113
	v_pk_mul_f32 v[154:155], v[102:103], v[146:147] op_sel_hi:[1,0]
	v_pk_mul_f32 v[106:107], v[106:107], v[146:147] op_sel_hi:[1,0]
	v_exp_f32_e32 v154, v154
	v_exp_f32_e32 v155, v155
	v_pk_mul_f32 v[108:109], v[108:109], v[146:147] op_sel_hi:[1,0]
	v_exp_f32_e32 v106, v106
	v_exp_f32_e32 v107, v107
	v_pk_fma_f32 v[114:115], v[142:143], v[114:115], v[142:143] op_sel_hi:[0,1,0]
	v_pk_mul_f32 v[180:181], v[104:105], v[146:147] op_sel_hi:[1,0]
	v_exp_f32_e32 v108, v108
	v_exp_f32_e32 v109, v109
	v_pk_fma_f32 v[116:117], v[142:143], v[116:117], v[142:143] op_sel_hi:[0,1,0]
	v_rcp_f32_e32 v114, v114
	v_rcp_f32_e32 v115, v115
	v_exp_f32_e32 v180, v180
	v_exp_f32_e32 v181, v181
	v_pk_fma_f32 v[110:111], v[142:143], v[110:111], v[142:143] op_sel_hi:[0,1,0]
	v_pk_fma_f32 v[112:113], v[142:143], v[112:113], v[142:143] op_sel_hi:[0,1,0]
	v_rcp_f32_e32 v116, v116
	v_rcp_f32_e32 v117, v117
	v_rcp_f32_e32 v110, v110
	v_rcp_f32_e32 v111, v111
	v_rcp_f32_e32 v112, v112
	v_rcp_f32_e32 v113, v113
	v_pk_fma_f32 v[142:143], v[144:145], v[154:155], v[144:145] op_sel_hi:[0,1,0]
	v_pk_fma_f32 v[106:107], v[144:145], v[106:107], v[144:145] op_sel_hi:[0,1,0]
	v_rcp_f32_e32 v142, v142
	v_rcp_f32_e32 v143, v143
	v_pk_fma_f32 v[108:109], v[144:145], v[108:109], v[144:145] op_sel_hi:[0,1,0]
	v_rcp_f32_e32 v154, v106
	v_rcp_f32_e32 v155, v107
	v_pk_mul_f32 v[106:107], v[156:157], v[114:115]
	v_pk_fma_f32 v[144:145], v[144:145], v[180:181], v[144:145] op_sel_hi:[0,1,0]
	v_rcp_f32_e32 v180, v108
	v_rcp_f32_e32 v181, v109
	v_pk_mul_f32 v[108:109], v[128:129], v[116:117]
	v_cvt_pk_bf16_f32 v106, v106, v107
	v_pk_mul_f32 v[110:111], v[172:173], v[110:111]
	v_cvt_pk_bf16_f32 v107, v108, v109
	v_pk_mul_f32 v[112:113], v[170:171], v[112:113]
	v_cvt_pk_bf16_f32 v108, v110, v111
	v_mov_b32_e32 v146, v179
	v_cvt_pk_bf16_f32 v109, v112, v113
	global_store_dwordx4 v141, v[106:109], s[8:9]
	v_pk_mul_f32 v[102:103], v[98:99], v[142:143]
	v_lshlrev_b64 v[98:99], s42, v[146:147]
	v_rcp_f32_e32 v106, v144
	v_rcp_f32_e32 v107, v145
	v_min_u32_e32 v98, 1, v98
	v_or_b32_e32 v98, v99, v98
	s_add_u32 s8, s43, s66
	v_pk_mul_f32 v[104:105], v[100:101], v[106:107]
	v_cvt_f32_u32_e32 v100, v178
	v_cvt_f32_u32_e32 v101, v98
	s_addc_u32 s9, s92, s67
	s_add_u32 s8, s8, s88
	v_fmamk_f32 v106, v100, 0x30000000, v209
	v_ldexp_f32 v100, v101, s93
	v_fmac_f32_e32 v106, 2.0, v100
	v_rsq_f32_e32 v107, v106
	v_pk_mul_f32 v[110:111], v[176:177], v[154:155]
	s_addc_u32 s9, s9, 0
	v_cvt_pk_bf16_f32 v98, v110, v111
	v_pk_mul_f32 v[112:113], v[174:175], v[180:181]
	v_mov_b32_e32 v146, v127
	v_cvt_pk_bf16_f32 v99, v112, v113
	v_cvt_pk_bf16_f32 v100, v102, v103
	v_cvt_pk_bf16_f32 v101, v104, v105
	global_store_dwordx4 v141, v[98:101], s[8:9]
	s_add_u32 s8, s43, s70
	s_addc_u32 s9, s92, s71
	v_mul_f32_e32 v98, 0xbfb8aa3b, v107
	v_pk_mul_f32 v[100:101], v[94:95], v[98:99] op_sel_hi:[1,0]
	v_pk_mul_f32 v[94:95], v[86:87], v[98:99] op_sel_hi:[1,0]
	v_pk_mul_f32 v[102:103], v[96:97], v[98:99] op_sel_hi:[1,0]
	v_exp_f32_e32 v94, v94
	v_exp_f32_e32 v95, v95
	v_pk_mul_f32 v[96:97], v[88:89], v[98:99] op_sel_hi:[1,0]
	v_exp_f32_e32 v100, v100
	v_exp_f32_e32 v96, v96
	v_exp_f32_e32 v97, v97
	v_pk_fma_f32 v[94:95], v[106:107], v[94:95], v[106:107] op_sel_hi:[0,1,0]
	v_rcp_f32_e32 v94, v94
	v_rcp_f32_e32 v95, v95
	v_exp_f32_e32 v101, v101
	v_pk_fma_f32 v[96:97], v[106:107], v[96:97], v[106:107] op_sel_hi:[0,1,0]
	v_rcp_f32_e32 v96, v96
	v_rcp_f32_e32 v97, v97
	v_pk_mul_f32 v[86:87], v[82:83], v[94:95]
	v_lshlrev_b64 v[82:83], s42, v[146:147]
	v_pk_fma_f32 v[100:101], v[106:107], v[100:101], v[106:107] op_sel_hi:[0,1,0]
	v_min_u32_e32 v82, 1, v82
	v_rcp_f32_e32 v100, v100
	v_rcp_f32_e32 v101, v101
	v_or_b32_e32 v82, v83, v82
	v_pk_mul_f32 v[88:89], v[84:85], v[96:97]
	v_cvt_f32_u32_e32 v84, v126
	v_cvt_f32_u32_e32 v85, v82
	v_exp_f32_e32 v102, v102
	v_exp_f32_e32 v103, v103
	v_pk_mul_f32 v[90:91], v[90:91], v[100:101]
	s_add_u32 s8, s8, s88
	v_cvt_pk_bf16_f32 v82, v90, v91
	v_fmamk_f32 v90, v84, 0x30000000, v209
	v_ldexp_f32 v84, v85, s93
	v_pk_fma_f32 v[102:103], v[106:107], v[102:103], v[106:107] op_sel_hi:[0,1,0]
	v_fmac_f32_e32 v90, 2.0, v84
	v_rcp_f32_e32 v102, v102
	v_rcp_f32_e32 v103, v103
	v_rsq_f32_e32 v91, v90
	s_addc_u32 s9, s9, 0
	v_mov_b32_e32 v146, v125
	v_pk_mul_f32 v[92:93], v[92:93], v[102:103]
	s_nop 0
	v_cvt_pk_bf16_f32 v83, v92, v93
	v_cvt_pk_bf16_f32 v84, v86, v87
	v_cvt_pk_bf16_f32 v85, v88, v89
	global_store_dwordx4 v141, v[82:85], s[8:9]
	s_add_u32 s8, s43, s26
	s_addc_u32 s9, s92, s27
	v_mul_f32_e32 v82, 0xbfb8aa3b, v91
	v_pk_mul_f32 v[84:85], v[78:79], v[82:83] op_sel_hi:[1,0]
	v_pk_mul_f32 v[78:79], v[70:71], v[82:83] op_sel_hi:[1,0]
	v_pk_mul_f32 v[86:87], v[80:81], v[82:83] op_sel_hi:[1,0]
	v_exp_f32_e32 v78, v78
	v_exp_f32_e32 v79, v79
	v_pk_mul_f32 v[80:81], v[72:73], v[82:83] op_sel_hi:[1,0]
	v_exp_f32_e32 v84, v84
	v_exp_f32_e32 v80, v80
	v_exp_f32_e32 v81, v81
	v_pk_fma_f32 v[78:79], v[90:91], v[78:79], v[90:91] op_sel_hi:[0,1,0]
	v_rcp_f32_e32 v78, v78
	v_rcp_f32_e32 v79, v79
	v_exp_f32_e32 v85, v85
	v_pk_fma_f32 v[80:81], v[90:91], v[80:81], v[90:91] op_sel_hi:[0,1,0]
	v_rcp_f32_e32 v80, v80
	v_rcp_f32_e32 v81, v81
	v_pk_mul_f32 v[70:71], v[66:67], v[78:79]
	v_lshlrev_b64 v[66:67], s42, v[146:147]
	v_pk_fma_f32 v[84:85], v[90:91], v[84:85], v[90:91] op_sel_hi:[0,1,0]
	v_min_u32_e32 v66, 1, v66
	v_rcp_f32_e32 v84, v84
	v_rcp_f32_e32 v85, v85
	v_or_b32_e32 v66, v67, v66
	v_pk_mul_f32 v[72:73], v[68:69], v[80:81]
	v_cvt_f32_u32_e32 v68, v124
	v_cvt_f32_u32_e32 v69, v66
	v_exp_f32_e32 v86, v86
	v_exp_f32_e32 v87, v87
	v_pk_mul_f32 v[74:75], v[74:75], v[84:85]
	s_add_u32 s8, s8, s88
	v_cvt_pk_bf16_f32 v66, v74, v75
	v_fmamk_f32 v74, v68, 0x30000000, v209
	v_ldexp_f32 v68, v69, s93
	v_pk_fma_f32 v[86:87], v[90:91], v[86:87], v[90:91] op_sel_hi:[0,1,0]
	v_fmac_f32_e32 v74, 2.0, v68
	v_rcp_f32_e32 v86, v86
	v_rcp_f32_e32 v87, v87
	v_rsq_f32_e32 v75, v74
	s_addc_u32 s9, s9, 0
	v_mov_b32_e32 v146, v123
	v_pk_mul_f32 v[76:77], v[76:77], v[86:87]
	s_nop 0
	v_cvt_pk_bf16_f32 v67, v76, v77
	v_cvt_pk_bf16_f32 v68, v70, v71
	v_cvt_pk_bf16_f32 v69, v72, v73
	global_store_dwordx4 v141, v[66:69], s[8:9]
	s_add_u32 s8, s43, s22
	s_addc_u32 s9, s92, s82
	v_mul_f32_e32 v66, 0xbfb8aa3b, v75
	v_pk_mul_f32 v[68:69], v[62:63], v[66:67] op_sel_hi:[1,0]
	v_pk_mul_f32 v[62:63], v[54:55], v[66:67] op_sel_hi:[1,0]
	v_pk_mul_f32 v[70:71], v[64:65], v[66:67] op_sel_hi:[1,0]
	v_exp_f32_e32 v62, v62
	v_exp_f32_e32 v63, v63
	v_pk_mul_f32 v[64:65], v[56:57], v[66:67] op_sel_hi:[1,0]
	v_exp_f32_e32 v68, v68
	v_exp_f32_e32 v64, v64
	v_exp_f32_e32 v65, v65
	v_pk_fma_f32 v[62:63], v[74:75], v[62:63], v[74:75] op_sel_hi:[0,1,0]
	v_rcp_f32_e32 v62, v62
	v_rcp_f32_e32 v63, v63
	v_exp_f32_e32 v69, v69
	v_pk_fma_f32 v[64:65], v[74:75], v[64:65], v[74:75] op_sel_hi:[0,1,0]
	v_rcp_f32_e32 v64, v64
	v_rcp_f32_e32 v65, v65
	v_pk_mul_f32 v[54:55], v[50:51], v[62:63]
	v_lshlrev_b64 v[50:51], s42, v[146:147]
	v_pk_fma_f32 v[68:69], v[74:75], v[68:69], v[74:75] op_sel_hi:[0,1,0]
	v_min_u32_e32 v50, 1, v50
	v_rcp_f32_e32 v68, v68
	v_rcp_f32_e32 v69, v69
	v_or_b32_e32 v50, v51, v50
	v_pk_mul_f32 v[56:57], v[52:53], v[64:65]
	v_cvt_f32_u32_e32 v52, v122
	v_cvt_f32_u32_e32 v53, v50
	v_exp_f32_e32 v70, v70
	v_exp_f32_e32 v71, v71
	v_pk_mul_f32 v[58:59], v[58:59], v[68:69]
	s_add_u32 s8, s8, s88
	v_cvt_pk_bf16_f32 v50, v58, v59
	v_fmamk_f32 v58, v52, 0x30000000, v209
	v_ldexp_f32 v52, v53, s93
	v_pk_fma_f32 v[70:71], v[74:75], v[70:71], v[74:75] op_sel_hi:[0,1,0]
	v_fmac_f32_e32 v58, 2.0, v52
	v_rcp_f32_e32 v70, v70
	v_rcp_f32_e32 v71, v71
	v_rsq_f32_e32 v59, v58
	s_addc_u32 s9, s9, 0
	v_mov_b32_e32 v146, v121
	v_pk_mul_f32 v[60:61], v[60:61], v[70:71]
	s_nop 0
	v_cvt_pk_bf16_f32 v51, v60, v61
	v_cvt_pk_bf16_f32 v52, v54, v55
	v_cvt_pk_bf16_f32 v53, v56, v57
	global_store_dwordx4 v141, v[50:53], s[8:9]
	s_add_u32 s8, s43, s12
	s_addc_u32 s9, s92, s83
	v_mul_f32_e32 v50, 0xbfb8aa3b, v59
	v_pk_mul_f32 v[52:53], v[46:47], v[50:51] op_sel_hi:[1,0]
	v_pk_mul_f32 v[46:47], v[38:39], v[50:51] op_sel_hi:[1,0]
	v_pk_mul_f32 v[54:55], v[48:49], v[50:51] op_sel_hi:[1,0]
	v_exp_f32_e32 v46, v46
	v_exp_f32_e32 v47, v47
	v_pk_mul_f32 v[48:49], v[40:41], v[50:51] op_sel_hi:[1,0]
	v_exp_f32_e32 v52, v52
	v_exp_f32_e32 v48, v48
	v_exp_f32_e32 v49, v49
	v_pk_fma_f32 v[46:47], v[58:59], v[46:47], v[58:59] op_sel_hi:[0,1,0]
	v_rcp_f32_e32 v46, v46
	v_rcp_f32_e32 v47, v47
	v_exp_f32_e32 v53, v53
	v_pk_fma_f32 v[48:49], v[58:59], v[48:49], v[58:59] op_sel_hi:[0,1,0]
	v_rcp_f32_e32 v48, v48
	v_rcp_f32_e32 v49, v49
	v_pk_mul_f32 v[38:39], v[34:35], v[46:47]
	v_lshlrev_b64 v[34:35], s42, v[146:147]
	v_pk_fma_f32 v[52:53], v[58:59], v[52:53], v[58:59] op_sel_hi:[0,1,0]
	v_min_u32_e32 v34, 1, v34
	v_rcp_f32_e32 v52, v52
	v_rcp_f32_e32 v53, v53
	v_or_b32_e32 v34, v35, v34
	v_pk_mul_f32 v[40:41], v[36:37], v[48:49]
	v_cvt_f32_u32_e32 v36, v120
	v_cvt_f32_u32_e32 v37, v34
	v_exp_f32_e32 v54, v54
	v_exp_f32_e32 v55, v55
	v_pk_mul_f32 v[42:43], v[42:43], v[52:53]
	s_add_u32 s8, s8, s88
	v_cvt_pk_bf16_f32 v34, v42, v43
	v_fmamk_f32 v42, v36, 0x30000000, v209
	v_ldexp_f32 v36, v37, s93
	v_pk_fma_f32 v[54:55], v[58:59], v[54:55], v[58:59] op_sel_hi:[0,1,0]
	v_fmac_f32_e32 v42, 2.0, v36
	v_rcp_f32_e32 v54, v54
	v_rcp_f32_e32 v55, v55
	v_rsq_f32_e32 v43, v42
	s_addc_u32 s9, s9, 0
	v_mov_b32_e32 v146, v119
	v_pk_mul_f32 v[44:45], v[44:45], v[54:55]
	s_nop 0
	v_cvt_pk_bf16_f32 v35, v44, v45
	v_cvt_pk_bf16_f32 v36, v38, v39
	v_cvt_pk_bf16_f32 v37, v40, v41
	global_store_dwordx4 v141, v[34:37], s[8:9]
	s_add_u32 s8, s43, s84
	s_addc_u32 s9, s92, s85
	v_mul_f32_e32 v34, 0xbfb8aa3b, v43
	v_pk_mul_f32 v[36:37], v[30:31], v[34:35] op_sel_hi:[1,0]
	v_pk_mul_f32 v[30:31], v[22:23], v[34:35] op_sel_hi:[1,0]
	v_pk_mul_f32 v[38:39], v[32:33], v[34:35] op_sel_hi:[1,0]
	v_exp_f32_e32 v30, v30
	v_exp_f32_e32 v31, v31
	v_pk_mul_f32 v[32:33], v[24:25], v[34:35] op_sel_hi:[1,0]
	v_exp_f32_e32 v36, v36
	v_exp_f32_e32 v32, v32
	v_exp_f32_e32 v33, v33
	v_pk_fma_f32 v[30:31], v[42:43], v[30:31], v[42:43] op_sel_hi:[0,1,0]
	v_rcp_f32_e32 v30, v30
	v_rcp_f32_e32 v31, v31
	v_exp_f32_e32 v37, v37
	v_pk_fma_f32 v[32:33], v[42:43], v[32:33], v[42:43] op_sel_hi:[0,1,0]
	v_rcp_f32_e32 v32, v32
	v_rcp_f32_e32 v33, v33
	v_pk_mul_f32 v[22:23], v[18:19], v[30:31]
	v_lshlrev_b64 v[18:19], s42, v[146:147]
	v_pk_fma_f32 v[36:37], v[42:43], v[36:37], v[42:43] op_sel_hi:[0,1,0]
	v_min_u32_e32 v18, 1, v18
	v_rcp_f32_e32 v36, v36
	v_rcp_f32_e32 v37, v37
	v_or_b32_e32 v18, v19, v18
	v_pk_mul_f32 v[24:25], v[20:21], v[32:33]
	v_cvt_f32_u32_e32 v20, v118
	v_cvt_f32_u32_e32 v21, v18
	v_exp_f32_e32 v38, v38
	v_exp_f32_e32 v39, v39
	v_pk_mul_f32 v[26:27], v[26:27], v[36:37]
	s_add_u32 s8, s8, s88
	v_cvt_pk_bf16_f32 v18, v26, v27
	v_fmamk_f32 v26, v20, 0x30000000, v209
	v_ldexp_f32 v20, v21, s93
	v_pk_fma_f32 v[38:39], v[42:43], v[38:39], v[42:43] op_sel_hi:[0,1,0]
	v_fmac_f32_e32 v26, 2.0, v20
	v_rcp_f32_e32 v38, v38
	v_rcp_f32_e32 v39, v39
	v_rsq_f32_e32 v27, v26
	s_addc_u32 s9, s9, 0
	v_pk_mul_f32 v[28:29], v[28:29], v[38:39]
	s_nop 0
	v_cvt_pk_bf16_f32 v19, v28, v29
	v_cvt_pk_bf16_f32 v20, v22, v23
	v_cvt_pk_bf16_f32 v21, v24, v25
	global_store_dwordx4 v141, v[18:21], s[8:9]
	s_add_u32 s8, s43, s86
	s_addc_u32 s9, s92, s87
	v_mul_f32_e32 v18, 0xbfb8aa3b, v27
	v_pk_mul_f32 v[20:21], v[14:15], v[18:19] op_sel_hi:[1,0]
	v_pk_mul_f32 v[22:23], v[16:17], v[18:19] op_sel_hi:[1,0]
	v_pk_mul_f32 v[14:15], v[6:7], v[18:19] op_sel_hi:[1,0]
	v_pk_mul_f32 v[16:17], v[8:9], v[18:19] op_sel_hi:[1,0]
	v_exp_f32_e32 v20, v20
	v_exp_f32_e32 v21, v21
	v_exp_f32_e32 v22, v22
	v_exp_f32_e32 v23, v23
	v_exp_f32_e32 v14, v14
	v_exp_f32_e32 v15, v15
	v_exp_f32_e32 v16, v16
	v_exp_f32_e32 v17, v17
	v_pk_fma_f32 v[20:21], v[26:27], v[20:21], v[26:27] op_sel_hi:[0,1,0]
	v_pk_fma_f32 v[22:23], v[26:27], v[22:23], v[26:27] op_sel_hi:[0,1,0]
	v_pk_fma_f32 v[14:15], v[26:27], v[14:15], v[26:27] op_sel_hi:[0,1,0]
	v_pk_fma_f32 v[16:17], v[26:27], v[16:17], v[26:27] op_sel_hi:[0,1,0]
	v_rcp_f32_e32 v20, v20
	v_rcp_f32_e32 v21, v21
	v_rcp_f32_e32 v22, v22
	v_rcp_f32_e32 v23, v23
	v_rcp_f32_e32 v14, v14
	v_rcp_f32_e32 v15, v15
	v_rcp_f32_e32 v16, v16
	v_rcp_f32_e32 v17, v17
	s_add_u32 s8, s8, s88
	s_addc_u32 s9, s9, 0
	v_pk_mul_f32 v[10:11], v[10:11], v[20:21]
	v_pk_mul_f32 v[12:13], v[12:13], v[22:23]
	v_pk_mul_f32 v[6:7], v[2:3], v[14:15]
	v_pk_mul_f32 v[8:9], v[4:5], v[16:17]
	v_cvt_pk_bf16_f32 v2, v10, v11
	v_cvt_pk_bf16_f32 v3, v12, v13
	v_cvt_pk_bf16_f32 v4, v6, v7
	s_andn2_b64 vcc, exec, s[34:35]
	v_cvt_pk_bf16_f32 v5, v8, v9
	global_store_dwordx4 v141, v[2:5], s[8:9]
	s_mov_b64 s[8:9], -1
	s_cbranch_vccnz .LBB0_293
	s_andn2_b64 vcc, exec, s[44:45]
	s_cbranch_vccnz .LBB0_292
	s_barrier
	s_branch .LBB0_292

.LBB0_1879:
	s_lshl_b32 s18, s91, 20
	s_and_b64 s[8:9], s[48:49], exec
	s_cselect_b32 s8, s18, s95
	s_lshl_b32 s19, s92, 20
	s_and_b64 s[42:43], s[48:49], exec
	s_cselect_b32 s9, s19, s94
	s_add_i32 vcc_lo, s95, 0x80080
	s_add_i32 vcc_hi, s94, 0x100
	s_mov_b32 s94, -2
	v_mbcnt_lo_u32_b32 v206, -1, 0
	v_mbcnt_hi_u32_b32 v206, -1, v206
	s_add_i32 s43, s72, 0x16000
	v_and_b32_e32 v207, 31, v206
	v_and_b32_e32 v208, 32, v206
	v_and_b32_e32 v206, 15, v206
	s_mov_b32 m0, s43
	v_lshlrev_b32_e32 v207, 4, v207
	v_lshlrev_b32_e32 v206, 3, v206
	v_lshl_or_b32 v207, v208, 5, v207
	v_add_u32_e32 v206, s43, v206
	s_lshl_b32 s42, s93, 8
	s_add_i32 s42, s42, s46
	s_lshl_b32 s42, s42, 3
	v_readlane_b32 s43, v255, 57
	s_nop 0
	s_add_u32 s42, s43, s42
	v_readlane_b32 s43, v255, 58
	s_nop 0
	s_addc_u32 s43, s43, 0
	global_load_lds_dwordx4 v207, s[42:43]
	v_add_u32_e32 v139, 0x10000, v136
	ds_read_b128 v[140:143], v139
	ds_read_b128 v[154:157], v139 offset:1024
	ds_read_b128 v[170:173], v139 offset:2048
	ds_read_b128 v[174:177], v139 offset:3072
	v_add_u32_e32 v139, 0x14000, v136
	ds_read_b128 v[178:181], v139
	ds_read_b128 v[182:185], v139 offset:1024
	ds_read_b128 v[186:189], v139 offset:2048
	ds_read_b128 v[190:193], v139 offset:3072
	s_add_i32 s42, vcc_lo, 0xfff80080
	s_cmp_eq_u32 s94, 28
	s_cselect_b32 s52, s8, s42
	s_cselect_b32 s96, s9, vcc_hi
	s_or_b32 s95, s52, 0x80
	s_mov_b32 m0, s72
	ds_read_b128 v[194:197], v137
	ds_read_b128 v[198:201], v137 offset:1024
	ds_read_b128 v[202:205], v137 offset:2048
	ds_read_b128 v[228:231], v137 offset:3072
	ds_read_b128 v[232:235], v137 offset:4096
	ds_read_b128 v[236:239], v137 offset:5120
	ds_read_b128 v[240:243], v137 offset:6144
	ds_read_b128 v[244:247], v137 offset:7168
	buffer_load_dwordx4 v132, s[60:63], vcc_lo offen lds
	s_mov_b32 m0, s47
	s_nop 0
	buffer_load_dwordx4 v134, s[60:63], vcc_lo offen lds
	s_waitcnt vmcnt(8)
	s_waitcnt lgkmcnt(0)
	s_setprio 1
	s_barrier
	v_mfma_f32_16x16x32_bf16 v[114:117], v[140:143], v[194:197], 0
	v_mfma_f32_16x16x32_bf16 v[114:117], v[154:157], v[198:201], v[114:117]
	v_mfma_f32_16x16x32_bf16 v[110:113], v[170:173], v[194:197], 0
	v_mfma_f32_16x16x32_bf16 v[110:113], v[174:177], v[198:201], v[110:113]
	v_mfma_f32_16x16x32_bf16 v[122:125], v[186:189], v[194:197], 0
	v_mfma_f32_16x16x32_bf16 v[122:125], v[190:193], v[198:201], v[122:125]
	v_mfma_f32_16x16x32_bf16 v[126:129], v[178:181], v[194:197], 0
	v_mfma_f32_16x16x32_bf16 v[126:129], v[182:185], v[198:201], v[126:129]
	v_mfma_f32_16x16x32_bf16 v[118:121], v[178:181], v[202:205], 0
	v_mfma_f32_16x16x32_bf16 v[118:121], v[182:185], v[228:231], v[118:121]
	v_mfma_f32_16x16x32_bf16 v[98:101], v[186:189], v[202:205], 0
	v_mfma_f32_16x16x32_bf16 v[98:101], v[190:193], v[228:231], v[98:101]
	v_mfma_f32_16x16x32_bf16 v[102:105], v[170:173], v[202:205], 0
	v_mfma_f32_16x16x32_bf16 v[102:105], v[174:177], v[228:231], v[102:105]
	v_mfma_f32_16x16x32_bf16 v[106:109], v[140:143], v[202:205], 0
	v_mfma_f32_16x16x32_bf16 v[106:109], v[154:157], v[228:231], v[106:109]
	v_mfma_f32_16x16x32_bf16 v[94:97], v[140:143], v[232:235], 0
	v_mfma_f32_16x16x32_bf16 v[94:97], v[154:157], v[236:239], v[94:97]
	v_mfma_f32_16x16x32_bf16 v[86:89], v[170:173], v[232:235], 0
	v_mfma_f32_16x16x32_bf16 v[86:89], v[174:177], v[236:239], v[86:89]
	v_mfma_f32_16x16x32_bf16 v[82:85], v[186:189], v[232:235], 0
	v_mfma_f32_16x16x32_bf16 v[82:85], v[190:193], v[236:239], v[82:85]
	v_mfma_f32_16x16x32_bf16 v[90:93], v[178:181], v[232:235], 0
	v_mfma_f32_16x16x32_bf16 v[90:93], v[182:185], v[236:239], v[90:93]
	v_mfma_f32_16x16x32_bf16 v[74:77], v[178:181], v[240:243], 0
	v_mfma_f32_16x16x32_bf16 v[74:77], v[182:185], v[244:247], v[74:77]
	v_mfma_f32_16x16x32_bf16 v[66:69], v[186:189], v[240:243], 0
	v_mfma_f32_16x16x32_bf16 v[66:69], v[190:193], v[244:247], v[66:69]
	v_mfma_f32_16x16x32_bf16 v[70:73], v[170:173], v[240:243], 0
	v_mfma_f32_16x16x32_bf16 v[70:73], v[174:177], v[244:247], v[70:73]
	v_mfma_f32_16x16x32_bf16 v[78:81], v[140:143], v[240:243], 0
	v_mfma_f32_16x16x32_bf16 v[78:81], v[154:157], v[244:247], v[78:81]
	s_barrier
	s_setprio 0
	s_mov_b32 s42, s62
	s_mov_b32 s43, s63
	s_mov_b32 m0, s13
	ds_read_b128 v[194:197], v137 offset:16384
	buffer_load_dwordx4 v133, s[40:43], s96 offen lds
	s_add_i32 s53, s96, 0x80000
	s_mov_b32 m0, s14
	ds_read_b128 v[198:201], v137 offset:17408
	buffer_load_dwordx4 v135, s[40:43], s96 offen lds
	s_mov_b32 m0, s15
	ds_read_b128 v[202:205], v137 offset:18432
	buffer_load_dwordx4 v133, s[40:43], s53 offen lds
	s_mov_b32 m0, s16
	ds_read_b128 v[228:231], v137 offset:19456
	buffer_load_dwordx4 v135, s[40:43], s53 offen lds
	s_mov_b32 m0, s2
	ds_read_b128 v[232:235], v137 offset:20480
	buffer_load_dwordx4 v132, s[60:63], s52 offen lds
	s_mov_b32 m0, s21
	ds_read_b128 v[236:239], v137 offset:21504
	buffer_load_dwordx4 v134, s[60:63], s52 offen lds
	ds_read_b128 v[240:243], v137 offset:22528
	ds_read_b128 v[244:247], v137 offset:23552
	s_waitcnt vmcnt(8)
	s_waitcnt lgkmcnt(0)
	s_setprio 1
	s_barrier
	v_mfma_f32_16x16x32_bf16 v[62:65], v[140:143], v[194:197], 0
	v_mfma_f32_16x16x32_bf16 v[62:65], v[154:157], v[198:201], v[62:65]
	v_mfma_f32_16x16x32_bf16 v[54:57], v[170:173], v[194:197], 0
	v_mfma_f32_16x16x32_bf16 v[54:57], v[174:177], v[198:201], v[54:57]
	v_mfma_f32_16x16x32_bf16 v[50:53], v[186:189], v[194:197], 0
	v_mfma_f32_16x16x32_bf16 v[50:53], v[190:193], v[198:201], v[50:53]
	v_mfma_f32_16x16x32_bf16 v[58:61], v[178:181], v[194:197], 0
	v_mfma_f32_16x16x32_bf16 v[58:61], v[182:185], v[198:201], v[58:61]
	v_mfma_f32_16x16x32_bf16 v[42:45], v[178:181], v[202:205], 0
	v_mfma_f32_16x16x32_bf16 v[42:45], v[182:185], v[228:231], v[42:45]
	v_mfma_f32_16x16x32_bf16 v[34:37], v[186:189], v[202:205], 0
	v_mfma_f32_16x16x32_bf16 v[34:37], v[190:193], v[228:231], v[34:37]
	v_mfma_f32_16x16x32_bf16 v[38:41], v[170:173], v[202:205], 0
	v_mfma_f32_16x16x32_bf16 v[38:41], v[174:177], v[228:231], v[38:41]
	v_mfma_f32_16x16x32_bf16 v[46:49], v[140:143], v[202:205], 0
	v_mfma_f32_16x16x32_bf16 v[46:49], v[154:157], v[228:231], v[46:49]
	v_mfma_f32_16x16x32_bf16 v[30:33], v[140:143], v[232:235], 0
	v_mfma_f32_16x16x32_bf16 v[30:33], v[154:157], v[236:239], v[30:33]
	v_mfma_f32_16x16x32_bf16 v[22:25], v[170:173], v[232:235], 0
	v_mfma_f32_16x16x32_bf16 v[22:25], v[174:177], v[236:239], v[22:25]
	v_mfma_f32_16x16x32_bf16 v[18:21], v[186:189], v[232:235], 0
	v_mfma_f32_16x16x32_bf16 v[18:21], v[190:193], v[236:239], v[18:21]
	v_mfma_f32_16x16x32_bf16 v[26:29], v[178:181], v[232:235], 0
	v_mfma_f32_16x16x32_bf16 v[26:29], v[182:185], v[236:239], v[26:29]
	v_mfma_f32_16x16x32_bf16 v[10:13], v[178:181], v[240:243], 0
	v_mfma_f32_16x16x32_bf16 v[10:13], v[182:185], v[244:247], v[10:13]
	v_mfma_f32_16x16x32_bf16 v[2:5], v[186:189], v[240:243], 0
	v_mfma_f32_16x16x32_bf16 v[2:5], v[190:193], v[244:247], v[2:5]
	v_mfma_f32_16x16x32_bf16 v[6:9], v[170:173], v[240:243], 0
	v_mfma_f32_16x16x32_bf16 v[6:9], v[174:177], v[244:247], v[6:9]
	v_mfma_f32_16x16x32_bf16 v[14:17], v[140:143], v[240:243], 0
	v_mfma_f32_16x16x32_bf16 v[14:17], v[154:157], v[244:247], v[14:17]
	s_barrier
	s_setprio 0
	v_add_u32_e32 v139, 0x18000, v136
	ds_read_b128 v[140:143], v139
	ds_read_b128 v[154:157], v139 offset:1024
	ds_read_b128 v[170:173], v139 offset:2048
	ds_read_b128 v[174:177], v139 offset:3072
	v_add_u32_e32 v139, 0x1c000, v136
	ds_read_b128 v[178:181], v139
	ds_read_b128 v[182:185], v139 offset:1024
	ds_read_b128 v[186:189], v139 offset:2048
	ds_read_b128 v[190:193], v139 offset:3072
	s_add_i32 s52, s52, 0x80000
	s_mov_b32 m0, s23
	ds_read_b128 v[194:197], v137 offset:32768
	ds_read_b128 v[198:201], v137 offset:33792
	ds_read_b128 v[202:205], v137 offset:34816
	ds_read_b128 v[228:231], v137 offset:35840
	ds_read_b128 v[232:235], v137 offset:36864
	ds_read_b128 v[236:239], v137 offset:37888
	ds_read_b128 v[240:243], v137 offset:38912
	ds_read_b128 v[244:247], v137 offset:39936
	buffer_load_dwordx4 v132, s[60:63], s52 offen lds
	s_mov_b32 m0, s24
	s_nop 0
	buffer_load_dwordx4 v134, s[60:63], s52 offen lds
	s_waitcnt vmcnt(8)
	s_waitcnt lgkmcnt(0)
	s_setprio 1
	s_barrier
	v_mfma_f32_16x16x32_bf16 v[114:117], v[140:143], v[194:197], v[114:117]
	v_mfma_f32_16x16x32_bf16 v[114:117], v[154:157], v[198:201], v[114:117]
	v_mfma_f32_16x16x32_bf16 v[110:113], v[170:173], v[194:197], v[110:113]
	v_mfma_f32_16x16x32_bf16 v[110:113], v[174:177], v[198:201], v[110:113]
	v_mfma_f32_16x16x32_bf16 v[122:125], v[186:189], v[194:197], v[122:125]
	v_mfma_f32_16x16x32_bf16 v[122:125], v[190:193], v[198:201], v[122:125]
	v_mfma_f32_16x16x32_bf16 v[126:129], v[178:181], v[194:197], v[126:129]
	v_mfma_f32_16x16x32_bf16 v[126:129], v[182:185], v[198:201], v[126:129]
	v_mfma_f32_16x16x32_bf16 v[118:121], v[178:181], v[202:205], v[118:121]
	v_mfma_f32_16x16x32_bf16 v[118:121], v[182:185], v[228:231], v[118:121]
	v_mfma_f32_16x16x32_bf16 v[98:101], v[186:189], v[202:205], v[98:101]
	v_mfma_f32_16x16x32_bf16 v[98:101], v[190:193], v[228:231], v[98:101]
	v_mfma_f32_16x16x32_bf16 v[102:105], v[170:173], v[202:205], v[102:105]
	v_mfma_f32_16x16x32_bf16 v[102:105], v[174:177], v[228:231], v[102:105]
	v_mfma_f32_16x16x32_bf16 v[106:109], v[140:143], v[202:205], v[106:109]
	v_mfma_f32_16x16x32_bf16 v[106:109], v[154:157], v[228:231], v[106:109]
	v_mfma_f32_16x16x32_bf16 v[94:97], v[140:143], v[232:235], v[94:97]
	v_mfma_f32_16x16x32_bf16 v[94:97], v[154:157], v[236:239], v[94:97]
	v_mfma_f32_16x16x32_bf16 v[86:89], v[170:173], v[232:235], v[86:89]
	v_mfma_f32_16x16x32_bf16 v[86:89], v[174:177], v[236:239], v[86:89]
	v_mfma_f32_16x16x32_bf16 v[82:85], v[186:189], v[232:235], v[82:85]
	v_mfma_f32_16x16x32_bf16 v[82:85], v[190:193], v[236:239], v[82:85]
	v_mfma_f32_16x16x32_bf16 v[90:93], v[178:181], v[232:235], v[90:93]
	v_mfma_f32_16x16x32_bf16 v[90:93], v[182:185], v[236:239], v[90:93]
	v_mfma_f32_16x16x32_bf16 v[74:77], v[178:181], v[240:243], v[74:77]
	v_mfma_f32_16x16x32_bf16 v[74:77], v[182:185], v[244:247], v[74:77]
	v_mfma_f32_16x16x32_bf16 v[66:69], v[186:189], v[240:243], v[66:69]
	v_mfma_f32_16x16x32_bf16 v[66:69], v[190:193], v[244:247], v[66:69]
	v_mfma_f32_16x16x32_bf16 v[70:73], v[170:173], v[240:243], v[70:73]
	v_mfma_f32_16x16x32_bf16 v[70:73], v[174:177], v[244:247], v[70:73]
	v_mfma_f32_16x16x32_bf16 v[78:81], v[140:143], v[240:243], v[78:81]
	v_mfma_f32_16x16x32_bf16 v[78:81], v[154:157], v[244:247], v[78:81]
	s_barrier
	s_setprio 0
	s_or_b32 s52, s96, 0x80
	s_mov_b32 m0, s31
	ds_read_b128 v[194:197], v137 offset:49152
	buffer_load_dwordx4 v133, s[40:43], s52 offen lds
	s_add_i32 s96, s96, 0x80080
	s_mov_b32 m0, s33
	ds_read_b128 v[198:201], v137 offset:50176
	buffer_load_dwordx4 v135, s[40:43], s52 offen lds
	s_mov_b32 m0, s36
	ds_read_b128 v[202:205], v137 offset:51200
	buffer_load_dwordx4 v133, s[40:43], s96 offen lds
	s_mov_b32 m0, s37
	ds_read_b128 v[228:231], v137 offset:52224
	buffer_load_dwordx4 v135, s[40:43], s96 offen lds
	s_mov_b32 m0, s34
	ds_read_b128 v[232:235], v137 offset:53248
	buffer_load_dwordx4 v132, s[60:63], s95 offen lds
	s_mov_b32 m0, s35
	ds_read_b128 v[236:239], v137 offset:54272
	buffer_load_dwordx4 v134, s[60:63], s95 offen lds
	ds_read_b128 v[240:243], v137 offset:55296
	ds_read_b128 v[244:247], v137 offset:56320
	s_waitcnt vmcnt(8)
	s_waitcnt lgkmcnt(0)
	s_setprio 1
	s_barrier
	v_mfma_f32_16x16x32_bf16 v[62:65], v[140:143], v[194:197], v[62:65]
	v_mfma_f32_16x16x32_bf16 v[62:65], v[154:157], v[198:201], v[62:65]
	v_mfma_f32_16x16x32_bf16 v[54:57], v[170:173], v[194:197], v[54:57]
	v_mfma_f32_16x16x32_bf16 v[54:57], v[174:177], v[198:201], v[54:57]
	v_mfma_f32_16x16x32_bf16 v[50:53], v[186:189], v[194:197], v[50:53]
	v_mfma_f32_16x16x32_bf16 v[50:53], v[190:193], v[198:201], v[50:53]
	v_mfma_f32_16x16x32_bf16 v[58:61], v[178:181], v[194:197], v[58:61]
	v_mfma_f32_16x16x32_bf16 v[58:61], v[182:185], v[198:201], v[58:61]
	v_mfma_f32_16x16x32_bf16 v[42:45], v[178:181], v[202:205], v[42:45]
	v_mfma_f32_16x16x32_bf16 v[42:45], v[182:185], v[228:231], v[42:45]
	v_mfma_f32_16x16x32_bf16 v[34:37], v[186:189], v[202:205], v[34:37]
	v_mfma_f32_16x16x32_bf16 v[34:37], v[190:193], v[228:231], v[34:37]
	v_mfma_f32_16x16x32_bf16 v[38:41], v[170:173], v[202:205], v[38:41]
	v_mfma_f32_16x16x32_bf16 v[38:41], v[174:177], v[228:231], v[38:41]
	v_mfma_f32_16x16x32_bf16 v[46:49], v[140:143], v[202:205], v[46:49]
	v_mfma_f32_16x16x32_bf16 v[46:49], v[154:157], v[228:231], v[46:49]
	v_mfma_f32_16x16x32_bf16 v[30:33], v[140:143], v[232:235], v[30:33]
	v_mfma_f32_16x16x32_bf16 v[30:33], v[154:157], v[236:239], v[30:33]
	v_mfma_f32_16x16x32_bf16 v[22:25], v[170:173], v[232:235], v[22:25]
	v_mfma_f32_16x16x32_bf16 v[22:25], v[174:177], v[236:239], v[22:25]
	v_mfma_f32_16x16x32_bf16 v[18:21], v[186:189], v[232:235], v[18:21]
	v_mfma_f32_16x16x32_bf16 v[18:21], v[190:193], v[236:239], v[18:21]
	v_mfma_f32_16x16x32_bf16 v[26:29], v[178:181], v[232:235], v[26:29]
	v_mfma_f32_16x16x32_bf16 v[26:29], v[182:185], v[236:239], v[26:29]
	v_mfma_f32_16x16x32_bf16 v[10:13], v[178:181], v[240:243], v[10:13]
	v_mfma_f32_16x16x32_bf16 v[10:13], v[182:185], v[244:247], v[10:13]
	v_mfma_f32_16x16x32_bf16 v[2:5], v[186:189], v[240:243], v[2:5]
	v_mfma_f32_16x16x32_bf16 v[2:5], v[190:193], v[244:247], v[2:5]
	v_mfma_f32_16x16x32_bf16 v[6:9], v[170:173], v[240:243], v[6:9]
	v_mfma_f32_16x16x32_bf16 v[6:9], v[174:177], v[244:247], v[6:9]
	v_mfma_f32_16x16x32_bf16 v[14:17], v[140:143], v[240:243], v[14:17]
	v_mfma_f32_16x16x32_bf16 v[14:17], v[154:157], v[244:247], v[14:17]
	s_barrier
	s_setprio 0
	s_add_i32 s94, s94, 2
	s_addk_i32 vcc_lo, 0x100
	s_addk_i32 vcc_hi, 0x100
	s_cmp_gt_u32 s94, 29

.LBB0_1883:
	s_lshl_b32 s8, s93, 8
	s_add_i32 s8, s8, s46
	s_ashr_i32 s9, s8, 31
	v_lshl_add_u64 v[140:141], s[8:9], 3, v[130:131]
	ds_read_b64 v[142:143], v206
	ds_read_b64 v[144:145], v206 offset:128
	v_pk_mul_f32 v[154:155], v[114:115], v[126:127]
	v_pk_mul_f32 v[156:157], v[112:113], v[124:125]
	v_pk_mul_f32 v[170:171], v[110:111], v[122:123]
	v_pk_mul_f32 v[172:173], v[108:109], v[120:121]
	v_pk_mul_f32 v[174:175], v[106:107], v[118:119]
	ds_read_b64 v[176:177], v206 offset:256
	ds_read_b64 v[126:127], v206 offset:384
	ds_read_b64 v[124:125], v206 offset:512
	ds_read_b64 v[122:123], v206 offset:640
	ds_read_b64 v[120:121], v206 offset:768
	ds_read_b64 v[118:119], v206 offset:896
	s_flbit_i32_b32 s8, 0
	s_min_u32 s42, s8, 32
	s_mul_i32 s8, s93, 0x58
	s_sub_i32 s93, 32, s42
	v_pk_mul_f32 v[128:129], v[116:117], v[128:129]
	s_lshl_b32 s9, s90, 1
	s_or_b32 s9, s9, s73
	s_add_i32 s8, s9, s8
	s_ashr_i32 s9, s8, 31
	s_lshl_b64 s[8:9], s[8:9], 15
	s_add_u32 s43, s25, s8
	s_addc_u32 s90, s30, s9
	s_add_u32 s8, s43, s66
	s_addc_u32 s9, s90, s67
	s_add_u32 s8, s8, s88
	s_addc_u32 s9, s9, 0
	v_pk_mul_f32 v[98:99], v[102:103], v[98:99]
	v_pk_mul_f32 v[100:101], v[104:105], v[100:101]
	v_pk_mul_f32 v[90:91], v[94:95], v[90:91]
	v_pk_mul_f32 v[92:93], v[96:97], v[92:93]
	v_pk_mul_f32 v[82:83], v[86:87], v[82:83]
	v_pk_mul_f32 v[84:85], v[88:89], v[84:85]
	v_pk_mul_f32 v[74:75], v[78:79], v[74:75]
	v_pk_mul_f32 v[76:77], v[80:81], v[76:77]
	v_pk_mul_f32 v[66:67], v[70:71], v[66:67]
	v_pk_mul_f32 v[68:69], v[72:73], v[68:69]
	v_pk_mul_f32 v[58:59], v[62:63], v[58:59]
	v_pk_mul_f32 v[60:61], v[64:65], v[60:61]
	v_pk_mul_f32 v[50:51], v[54:55], v[50:51]
	v_pk_mul_f32 v[52:53], v[56:57], v[52:53]
	v_pk_mul_f32 v[42:43], v[46:47], v[42:43]
	v_pk_mul_f32 v[44:45], v[48:49], v[44:45]
	v_pk_mul_f32 v[34:35], v[38:39], v[34:35]
	v_pk_mul_f32 v[36:37], v[40:41], v[36:37]
	v_pk_mul_f32 v[26:27], v[30:31], v[26:27]
	v_pk_mul_f32 v[28:29], v[32:33], v[28:29]
	v_pk_mul_f32 v[18:19], v[22:23], v[18:19]
	v_pk_mul_f32 v[20:21], v[24:25], v[20:21]
	v_pk_mul_f32 v[12:13], v[16:17], v[12:13]
	v_pk_mul_f32 v[10:11], v[14:15], v[10:11]
	v_pk_mul_f32 v[4:5], v[8:9], v[4:5]
	v_pk_mul_f32 v[2:3], v[6:7], v[2:3]
	v_readlane_b32 s96, v252, 46
	s_waitcnt lgkmcnt(0)
	v_cvt_f32_u32_e32 v139, v142
	v_mov_b32_e32 v146, v143
	v_lshlrev_b64 v[140:141], s42, v[146:147]
	v_min_u32_e32 v140, 1, v140
	v_mov_b32_e32 v146, v145
	v_or_b32_e32 v141, v141, v140
	v_lshlrev_b64 v[142:143], s42, v[146:147]
	v_fmamk_f32 v140, v139, 0x30000000, v209
	v_cvt_f32_u32_e32 v139, v141
	v_min_u32_e32 v145, 1, v142
	v_or_b32_e32 v141, v143, v145
	v_cvt_f32_u32_e32 v144, v144
	v_cvt_f32_u32_e32 v141, v141
	v_ldexp_f32 v139, v139, s93
	v_fmac_f32_e32 v140, 2.0, v139
	v_rsq_f32_e32 v139, v140
	v_fmamk_f32 v142, v144, 0x30000000, v209
	v_ldexp_f32 v141, v141, s93
	v_fmac_f32_e32 v142, 2.0, v141
	v_rsq_f32_e32 v141, v142
	v_mul_f32_e32 v144, 0xbfb8aa3b, v139
	v_pk_mul_f32 v[114:115], v[114:115], v[144:145] op_sel_hi:[1,0]
	v_pk_mul_f32 v[116:117], v[116:117], v[144:145] op_sel_hi:[1,0]
	v_exp_f32_e32 v114, v114
	v_exp_f32_e32 v115, v115
	v_pk_mul_f32 v[110:111], v[110:111], v[144:145] op_sel_hi:[1,0]
	v_pk_mul_f32 v[112:113], v[112:113], v[144:145] op_sel_hi:[1,0]
	v_mul_f32_e32 v144, 0xbfb8aa3b, v141
	v_exp_f32_e32 v116, v116
	v_exp_f32_e32 v117, v117
	v_exp_f32_e32 v110, v110
	v_exp_f32_e32 v111, v111
	v_exp_f32_e32 v112, v112
	v_exp_f32_e32 v113, v113
	v_pk_mul_f32 v[178:179], v[102:103], v[144:145] op_sel_hi:[1,0]
	v_pk_mul_f32 v[106:107], v[106:107], v[144:145] op_sel_hi:[1,0]
	v_exp_f32_e32 v178, v178
	v_exp_f32_e32 v179, v179
	v_pk_mul_f32 v[108:109], v[108:109], v[144:145] op_sel_hi:[1,0]
	v_pk_mul_f32 v[144:145], v[104:105], v[144:145] op_sel_hi:[1,0]
	v_exp_f32_e32 v106, v106
	v_exp_f32_e32 v107, v107
	v_pk_fma_f32 v[114:115], v[140:141], v[114:115], v[140:141] op_sel_hi:[0,1,0]
	v_exp_f32_e32 v108, v108
	v_exp_f32_e32 v109, v109
	v_exp_f32_e32 v144, v144
	v_exp_f32_e32 v145, v145
	v_pk_fma_f32 v[116:117], v[140:141], v[116:117], v[140:141] op_sel_hi:[0,1,0]
	v_rcp_f32_e32 v114, v114
	v_rcp_f32_e32 v115, v115
	v_pk_fma_f32 v[110:111], v[140:141], v[110:111], v[140:141] op_sel_hi:[0,1,0]
	v_pk_fma_f32 v[112:113], v[140:141], v[112:113], v[140:141] op_sel_hi:[0,1,0]
	v_rcp_f32_e32 v116, v116
	v_rcp_f32_e32 v117, v117
	v_rcp_f32_e32 v110, v110
	v_rcp_f32_e32 v111, v111
	v_rcp_f32_e32 v112, v112
	v_rcp_f32_e32 v113, v113
	v_pk_fma_f32 v[140:141], v[142:143], v[178:179], v[142:143] op_sel_hi:[0,1,0]
	v_pk_fma_f32 v[106:107], v[142:143], v[106:107], v[142:143] op_sel_hi:[0,1,0]
	v_rcp_f32_e32 v140, v140
	v_rcp_f32_e32 v141, v141
	v_pk_fma_f32 v[108:109], v[142:143], v[108:109], v[142:143] op_sel_hi:[0,1,0]
	v_pk_fma_f32 v[142:143], v[142:143], v[144:145], v[142:143] op_sel_hi:[0,1,0]
	v_rcp_f32_e32 v144, v106
	v_rcp_f32_e32 v145, v107
	v_pk_mul_f32 v[106:107], v[154:155], v[114:115]
	v_rcp_f32_e32 v178, v108
	v_rcp_f32_e32 v179, v109
	v_pk_mul_f32 v[108:109], v[128:129], v[116:117]
	v_cvt_pk_bf16_f32 v106, v106, v107
	v_pk_mul_f32 v[110:111], v[170:171], v[110:111]
	v_cvt_pk_bf16_f32 v107, v108, v109
	v_pk_mul_f32 v[112:113], v[156:157], v[112:113]
	v_cvt_pk_bf16_f32 v108, v110, v111
	v_mov_b32_e32 v146, v177
	v_cvt_pk_bf16_f32 v109, v112, v113
	global_store_dwordx4 v138, v[106:109], s[8:9]
	v_pk_mul_f32 v[102:103], v[98:99], v[140:141]
	v_lshlrev_b64 v[98:99], s42, v[146:147]
	v_rcp_f32_e32 v106, v142
	v_rcp_f32_e32 v107, v143
	v_min_u32_e32 v98, 1, v98
	v_or_b32_e32 v98, v99, v98
	s_add_u32 s8, s43, s68
	v_pk_mul_f32 v[104:105], v[100:101], v[106:107]
	v_cvt_f32_u32_e32 v100, v176
	v_cvt_f32_u32_e32 v101, v98
	s_addc_u32 s9, s90, s69
	s_add_u32 s8, s8, s88
	v_fmamk_f32 v106, v100, 0x30000000, v209
	v_ldexp_f32 v100, v101, s93
	v_fmac_f32_e32 v106, 2.0, v100
	v_rsq_f32_e32 v107, v106
	v_pk_mul_f32 v[110:111], v[174:175], v[144:145]
	s_addc_u32 s9, s9, 0
	v_cvt_pk_bf16_f32 v98, v110, v111
	v_pk_mul_f32 v[112:113], v[172:173], v[178:179]
	v_mov_b32_e32 v146, v127
	v_cvt_pk_bf16_f32 v99, v112, v113
	v_cvt_pk_bf16_f32 v100, v102, v103
	v_cvt_pk_bf16_f32 v101, v104, v105
	global_store_dwordx4 v138, v[98:101], s[8:9]
	s_add_u32 s8, s43, s70
	s_addc_u32 s9, s90, s71
	v_mul_f32_e32 v98, 0xbfb8aa3b, v107
	v_pk_mul_f32 v[100:101], v[94:95], v[98:99] op_sel_hi:[1,0]
	v_pk_mul_f32 v[94:95], v[86:87], v[98:99] op_sel_hi:[1,0]
	v_pk_mul_f32 v[102:103], v[96:97], v[98:99] op_sel_hi:[1,0]
	v_exp_f32_e32 v94, v94
	v_exp_f32_e32 v95, v95
	v_pk_mul_f32 v[96:97], v[88:89], v[98:99] op_sel_hi:[1,0]
	v_exp_f32_e32 v100, v100
	v_exp_f32_e32 v96, v96
	v_exp_f32_e32 v97, v97
	v_pk_fma_f32 v[94:95], v[106:107], v[94:95], v[106:107] op_sel_hi:[0,1,0]
	v_rcp_f32_e32 v94, v94
	v_rcp_f32_e32 v95, v95
	v_exp_f32_e32 v101, v101
	v_pk_fma_f32 v[96:97], v[106:107], v[96:97], v[106:107] op_sel_hi:[0,1,0]
	v_rcp_f32_e32 v96, v96
	v_rcp_f32_e32 v97, v97
	v_pk_mul_f32 v[86:87], v[82:83], v[94:95]
	v_lshlrev_b64 v[82:83], s42, v[146:147]
	v_pk_fma_f32 v[100:101], v[106:107], v[100:101], v[106:107] op_sel_hi:[0,1,0]
	v_min_u32_e32 v82, 1, v82
	v_rcp_f32_e32 v100, v100
	v_rcp_f32_e32 v101, v101
	v_or_b32_e32 v82, v83, v82
	v_pk_mul_f32 v[88:89], v[84:85], v[96:97]
	v_cvt_f32_u32_e32 v84, v126
	v_cvt_f32_u32_e32 v85, v82
	v_exp_f32_e32 v102, v102
	v_exp_f32_e32 v103, v103
	v_pk_mul_f32 v[90:91], v[90:91], v[100:101]
	s_add_u32 s8, s8, s88
	v_cvt_pk_bf16_f32 v82, v90, v91
	v_fmamk_f32 v90, v84, 0x30000000, v209
	v_ldexp_f32 v84, v85, s93
	v_pk_fma_f32 v[102:103], v[106:107], v[102:103], v[106:107] op_sel_hi:[0,1,0]
	v_fmac_f32_e32 v90, 2.0, v84
	v_rcp_f32_e32 v102, v102
	v_rcp_f32_e32 v103, v103
	v_rsq_f32_e32 v91, v90
	s_addc_u32 s9, s9, 0
	v_mov_b32_e32 v146, v125
	v_pk_mul_f32 v[92:93], v[92:93], v[102:103]
	s_nop 0
	v_cvt_pk_bf16_f32 v83, v92, v93
	v_cvt_pk_bf16_f32 v84, v86, v87
	v_cvt_pk_bf16_f32 v85, v88, v89
	global_store_dwordx4 v138, v[82:85], s[8:9]
	s_add_u32 s8, s43, s26
	s_addc_u32 s9, s90, s27
	v_mul_f32_e32 v82, 0xbfb8aa3b, v91
	v_pk_mul_f32 v[84:85], v[78:79], v[82:83] op_sel_hi:[1,0]
	v_pk_mul_f32 v[78:79], v[70:71], v[82:83] op_sel_hi:[1,0]
	v_pk_mul_f32 v[86:87], v[80:81], v[82:83] op_sel_hi:[1,0]
	v_exp_f32_e32 v78, v78
	v_exp_f32_e32 v79, v79
	v_pk_mul_f32 v[80:81], v[72:73], v[82:83] op_sel_hi:[1,0]
	v_exp_f32_e32 v84, v84
	v_exp_f32_e32 v80, v80
	v_exp_f32_e32 v81, v81
	v_pk_fma_f32 v[78:79], v[90:91], v[78:79], v[90:91] op_sel_hi:[0,1,0]
	v_rcp_f32_e32 v78, v78
	v_rcp_f32_e32 v79, v79
	v_exp_f32_e32 v85, v85
	v_pk_fma_f32 v[80:81], v[90:91], v[80:81], v[90:91] op_sel_hi:[0,1,0]
	v_rcp_f32_e32 v80, v80
	v_rcp_f32_e32 v81, v81
	v_pk_mul_f32 v[70:71], v[66:67], v[78:79]
	v_lshlrev_b64 v[66:67], s42, v[146:147]
	v_pk_fma_f32 v[84:85], v[90:91], v[84:85], v[90:91] op_sel_hi:[0,1,0]
	v_min_u32_e32 v66, 1, v66
	v_rcp_f32_e32 v84, v84
	v_rcp_f32_e32 v85, v85
	v_or_b32_e32 v66, v67, v66
	v_pk_mul_f32 v[72:73], v[68:69], v[80:81]
	v_cvt_f32_u32_e32 v68, v124
	v_cvt_f32_u32_e32 v69, v66
	v_exp_f32_e32 v86, v86
	v_exp_f32_e32 v87, v87
	v_pk_mul_f32 v[74:75], v[74:75], v[84:85]
	s_add_u32 s8, s8, s88
	v_cvt_pk_bf16_f32 v66, v74, v75
	v_fmamk_f32 v74, v68, 0x30000000, v209
	v_ldexp_f32 v68, v69, s93
	v_pk_fma_f32 v[86:87], v[90:91], v[86:87], v[90:91] op_sel_hi:[0,1,0]
	v_fmac_f32_e32 v74, 2.0, v68
	v_rcp_f32_e32 v86, v86
	v_rcp_f32_e32 v87, v87
	v_rsq_f32_e32 v75, v74
	s_addc_u32 s9, s9, 0
	v_mov_b32_e32 v146, v123
	v_pk_mul_f32 v[76:77], v[76:77], v[86:87]
	s_nop 0
	v_cvt_pk_bf16_f32 v67, v76, v77
	v_cvt_pk_bf16_f32 v68, v70, v71
	v_cvt_pk_bf16_f32 v69, v72, v73
	global_store_dwordx4 v138, v[66:69], s[8:9]
	s_add_u32 s8, s43, s82
	s_addc_u32 s9, s90, s84
	v_mul_f32_e32 v66, 0xbfb8aa3b, v75
	v_pk_mul_f32 v[68:69], v[62:63], v[66:67] op_sel_hi:[1,0]
	v_pk_mul_f32 v[62:63], v[54:55], v[66:67] op_sel_hi:[1,0]
	v_pk_mul_f32 v[70:71], v[64:65], v[66:67] op_sel_hi:[1,0]
	v_exp_f32_e32 v62, v62
	v_exp_f32_e32 v63, v63
	v_pk_mul_f32 v[64:65], v[56:57], v[66:67] op_sel_hi:[1,0]
	v_exp_f32_e32 v68, v68
	v_exp_f32_e32 v64, v64
	v_exp_f32_e32 v65, v65
	v_pk_fma_f32 v[62:63], v[74:75], v[62:63], v[74:75] op_sel_hi:[0,1,0]
	v_rcp_f32_e32 v62, v62
	v_rcp_f32_e32 v63, v63
	v_exp_f32_e32 v69, v69
	v_pk_fma_f32 v[64:65], v[74:75], v[64:65], v[74:75] op_sel_hi:[0,1,0]
	v_rcp_f32_e32 v64, v64
	v_rcp_f32_e32 v65, v65
	v_pk_mul_f32 v[54:55], v[50:51], v[62:63]
	v_lshlrev_b64 v[50:51], s42, v[146:147]
	v_pk_fma_f32 v[68:69], v[74:75], v[68:69], v[74:75] op_sel_hi:[0,1,0]
	v_min_u32_e32 v50, 1, v50
	v_rcp_f32_e32 v68, v68
	v_rcp_f32_e32 v69, v69
	v_or_b32_e32 v50, v51, v50
	v_pk_mul_f32 v[56:57], v[52:53], v[64:65]
	v_cvt_f32_u32_e32 v52, v122
	v_cvt_f32_u32_e32 v53, v50
	v_exp_f32_e32 v70, v70
	v_exp_f32_e32 v71, v71
	v_pk_mul_f32 v[58:59], v[58:59], v[68:69]
	s_add_u32 s8, s8, s88
	v_cvt_pk_bf16_f32 v50, v58, v59
	v_fmamk_f32 v58, v52, 0x30000000, v209
	v_ldexp_f32 v52, v53, s93
	v_pk_fma_f32 v[70:71], v[74:75], v[70:71], v[74:75] op_sel_hi:[0,1,0]
	v_fmac_f32_e32 v58, 2.0, v52
	v_rcp_f32_e32 v70, v70
	v_rcp_f32_e32 v71, v71
	v_rsq_f32_e32 v59, v58
	s_addc_u32 s9, s9, 0
	v_mov_b32_e32 v146, v121
	v_pk_mul_f32 v[60:61], v[60:61], v[70:71]
	s_nop 0
	v_cvt_pk_bf16_f32 v51, v60, v61
	v_cvt_pk_bf16_f32 v52, v54, v55
	v_cvt_pk_bf16_f32 v53, v56, v57
	global_store_dwordx4 v138, v[50:53], s[8:9]
	s_add_u32 s8, s43, s85
	s_addc_u32 s9, s90, s22
	v_mul_f32_e32 v50, 0xbfb8aa3b, v59
	v_pk_mul_f32 v[52:53], v[46:47], v[50:51] op_sel_hi:[1,0]
	v_pk_mul_f32 v[46:47], v[38:39], v[50:51] op_sel_hi:[1,0]
	v_pk_mul_f32 v[54:55], v[48:49], v[50:51] op_sel_hi:[1,0]
	v_exp_f32_e32 v46, v46
	v_exp_f32_e32 v47, v47
	v_pk_mul_f32 v[48:49], v[40:41], v[50:51] op_sel_hi:[1,0]
	v_exp_f32_e32 v52, v52
	v_exp_f32_e32 v48, v48
	v_exp_f32_e32 v49, v49
	v_pk_fma_f32 v[46:47], v[58:59], v[46:47], v[58:59] op_sel_hi:[0,1,0]
	v_rcp_f32_e32 v46, v46
	v_rcp_f32_e32 v47, v47
	v_exp_f32_e32 v53, v53
	v_pk_fma_f32 v[48:49], v[58:59], v[48:49], v[58:59] op_sel_hi:[0,1,0]
	v_rcp_f32_e32 v48, v48
	v_rcp_f32_e32 v49, v49
	v_pk_mul_f32 v[38:39], v[34:35], v[46:47]
	v_lshlrev_b64 v[34:35], s42, v[146:147]
	v_pk_fma_f32 v[52:53], v[58:59], v[52:53], v[58:59] op_sel_hi:[0,1,0]
	v_min_u32_e32 v34, 1, v34
	v_rcp_f32_e32 v52, v52
	v_rcp_f32_e32 v53, v53
	v_or_b32_e32 v34, v35, v34
	v_pk_mul_f32 v[40:41], v[36:37], v[48:49]
	v_cvt_f32_u32_e32 v36, v120
	v_cvt_f32_u32_e32 v37, v34
	v_exp_f32_e32 v54, v54
	v_exp_f32_e32 v55, v55
	v_pk_mul_f32 v[42:43], v[42:43], v[52:53]
	s_add_u32 s8, s8, s88
	v_cvt_pk_bf16_f32 v34, v42, v43
	v_fmamk_f32 v42, v36, 0x30000000, v209
	v_ldexp_f32 v36, v37, s93
	v_pk_fma_f32 v[54:55], v[58:59], v[54:55], v[58:59] op_sel_hi:[0,1,0]
	v_fmac_f32_e32 v42, 2.0, v36
	v_rcp_f32_e32 v54, v54
	v_rcp_f32_e32 v55, v55
	v_rsq_f32_e32 v43, v42
	s_addc_u32 s9, s9, 0
	v_mov_b32_e32 v146, v119
	v_pk_mul_f32 v[44:45], v[44:45], v[54:55]
	s_nop 0
	v_cvt_pk_bf16_f32 v35, v44, v45
	v_cvt_pk_bf16_f32 v36, v38, v39
	v_cvt_pk_bf16_f32 v37, v40, v41
	global_store_dwordx4 v138, v[34:37], s[8:9]
	s_add_u32 s8, s43, s83
	s_addc_u32 s9, s90, s12
	v_mul_f32_e32 v34, 0xbfb8aa3b, v43
	v_pk_mul_f32 v[36:37], v[30:31], v[34:35] op_sel_hi:[1,0]
	v_pk_mul_f32 v[30:31], v[22:23], v[34:35] op_sel_hi:[1,0]
	v_pk_mul_f32 v[38:39], v[32:33], v[34:35] op_sel_hi:[1,0]
	v_exp_f32_e32 v30, v30
	v_exp_f32_e32 v31, v31
	v_pk_mul_f32 v[32:33], v[24:25], v[34:35] op_sel_hi:[1,0]
	v_exp_f32_e32 v36, v36
	v_exp_f32_e32 v32, v32
	v_exp_f32_e32 v33, v33
	v_pk_fma_f32 v[30:31], v[42:43], v[30:31], v[42:43] op_sel_hi:[0,1,0]
	v_rcp_f32_e32 v30, v30
	v_rcp_f32_e32 v31, v31
	v_exp_f32_e32 v37, v37
	v_pk_fma_f32 v[32:33], v[42:43], v[32:33], v[42:43] op_sel_hi:[0,1,0]
	v_rcp_f32_e32 v32, v32
	v_rcp_f32_e32 v33, v33
	v_pk_mul_f32 v[22:23], v[18:19], v[30:31]
	v_lshlrev_b64 v[18:19], s42, v[146:147]
	v_pk_fma_f32 v[36:37], v[42:43], v[36:37], v[42:43] op_sel_hi:[0,1,0]
	v_min_u32_e32 v18, 1, v18
	v_rcp_f32_e32 v36, v36
	v_rcp_f32_e32 v37, v37
	v_or_b32_e32 v18, v19, v18
	v_pk_mul_f32 v[24:25], v[20:21], v[32:33]
	v_cvt_f32_u32_e32 v20, v118
	v_cvt_f32_u32_e32 v21, v18
	v_exp_f32_e32 v38, v38
	v_exp_f32_e32 v39, v39
	v_pk_mul_f32 v[26:27], v[26:27], v[36:37]
	s_add_u32 s8, s8, s88
	v_cvt_pk_bf16_f32 v18, v26, v27
	v_fmamk_f32 v26, v20, 0x30000000, v209
	v_ldexp_f32 v20, v21, s93
	v_pk_fma_f32 v[38:39], v[42:43], v[38:39], v[42:43] op_sel_hi:[0,1,0]
	v_fmac_f32_e32 v26, 2.0, v20
	v_rcp_f32_e32 v38, v38
	v_rcp_f32_e32 v39, v39
	v_rsq_f32_e32 v27, v26
	s_addc_u32 s9, s9, 0
	v_pk_mul_f32 v[28:29], v[28:29], v[38:39]
	s_nop 0
	v_cvt_pk_bf16_f32 v19, v28, v29
	v_cvt_pk_bf16_f32 v20, v22, v23
	v_cvt_pk_bf16_f32 v21, v24, v25
	global_store_dwordx4 v138, v[18:21], s[8:9]
	s_add_u32 s8, s43, s86
	s_addc_u32 s9, s90, s87
	v_mul_f32_e32 v18, 0xbfb8aa3b, v27
	v_pk_mul_f32 v[20:21], v[14:15], v[18:19] op_sel_hi:[1,0]
	v_pk_mul_f32 v[22:23], v[16:17], v[18:19] op_sel_hi:[1,0]
	v_pk_mul_f32 v[14:15], v[6:7], v[18:19] op_sel_hi:[1,0]
	v_pk_mul_f32 v[16:17], v[8:9], v[18:19] op_sel_hi:[1,0]
	v_exp_f32_e32 v20, v20
	v_exp_f32_e32 v21, v21
	v_exp_f32_e32 v22, v22
	v_exp_f32_e32 v23, v23
	v_exp_f32_e32 v14, v14
	v_exp_f32_e32 v15, v15
	v_exp_f32_e32 v16, v16
	v_exp_f32_e32 v17, v17
	v_pk_fma_f32 v[20:21], v[26:27], v[20:21], v[26:27] op_sel_hi:[0,1,0]
	v_pk_fma_f32 v[22:23], v[26:27], v[22:23], v[26:27] op_sel_hi:[0,1,0]
	v_pk_fma_f32 v[14:15], v[26:27], v[14:15], v[26:27] op_sel_hi:[0,1,0]
	v_pk_fma_f32 v[16:17], v[26:27], v[16:17], v[26:27] op_sel_hi:[0,1,0]
	v_rcp_f32_e32 v20, v20
	v_rcp_f32_e32 v21, v21
	v_rcp_f32_e32 v22, v22
	v_rcp_f32_e32 v23, v23
	v_rcp_f32_e32 v14, v14
	v_rcp_f32_e32 v15, v15
	v_rcp_f32_e32 v16, v16
	v_rcp_f32_e32 v17, v17
	s_add_u32 s8, s8, s88
	s_addc_u32 s9, s9, 0
	v_pk_mul_f32 v[10:11], v[10:11], v[20:21]
	v_pk_mul_f32 v[12:13], v[12:13], v[22:23]
	v_pk_mul_f32 v[6:7], v[2:3], v[14:15]
	v_pk_mul_f32 v[8:9], v[4:5], v[16:17]
	v_cvt_pk_bf16_f32 v2, v10, v11
	v_cvt_pk_bf16_f32 v3, v12, v13
	v_cvt_pk_bf16_f32 v4, v6, v7
	s_andn2_b64 vcc, exec, s[48:49]
	v_cvt_pk_bf16_f32 v5, v8, v9
	global_store_dwordx4 v138, v[2:5], s[8:9]
	s_mov_b64 s[8:9], -1
	s_cbranch_vccnz .LBB0_1869
	s_andn2_b64 vcc, exec, s[44:45]
	s_cbranch_vccnz .LBB0_1868
	s_barrier
	s_branch .LBB0_1868
